# prep moved into GEMM slack: Hyena filter items of layer l+1 run on workgroups idle in w_out/ffn_down/ffn_up(l), w_in/proj/w_out weight conversion on ffn_up(l) workgroups before their 4 tiles; norm1 ph
# speedup vs baseline: 1.0064x; 1.0062x over previous
_Z2mk6Paramsii:
	s_load_dwordx8 s[88:95], s[0:1], 0x140
	s_mov_b32 s101, 0
	s_movk_i32 s100, 0x790
	v_writelane_b32 v251, s2, 0
	s_add_u32 s2, s0, 0x168
	s_addc_u32 s3, s1, 0
	v_and_b32_e32 v135, 0x3ff, v0
	v_writelane_b32 v251, s2, 1
	v_mov_b32_e32 v1, v135
	s_nop 0
	v_writelane_b32 v251, s3, 2
	v_cmp_eq_u32_e32 vcc, 0, v1
	s_and_saveexec_b64 s[2:3], vcc
	v_mov_b32_e32 v2, 0
	v_mov_b32_e32 v3, v2
	v_mov_b32_e32 v4, v2
	v_mov_b32_e32 v5, v2
	ds_write_b128 v2, v[2:5] offset:64
	s_or_b64 exec, exec, s[2:3]
	s_load_dwordx2 s[84:85], s[0:1], 0x168
	s_waitcnt lgkmcnt(0)
	s_barrier
	s_add_u32 s4, s94, 0x169d6000
	s_getreg_b32 s2, hwreg(HW_REG_XCC_ID, 0, 4)
	v_mov_b32_e32 v1, v135
	s_addc_u32 s5, s95, 0
	s_and_b32 s8, s2, 15
	s_nop 0
	v_cmp_eq_u32_e32 vcc, 0, v1
	s_and_saveexec_b64 s[2:3], vcc
	s_cbranch_execz .LBB0_5
	s_mov_b64 s[6:7], exec
	v_mbcnt_lo_u32_b32 v1, s6, 0
	v_mbcnt_hi_u32_b32 v1, s7, v1
	v_cmp_eq_u32_e32 vcc, 0, v1
	s_and_b64 s[10:11], exec, vcc
	s_mov_b64 exec, s[10:11]
	s_cbranch_execz .LBB0_5
	s_lshl_b32 s9, s8, 8
	s_bcnt1_i32_b64 s6, s[6:7]
	v_mov_b32_e32 v1, s9
	v_mov_b32_e32 v2, s6
	global_atomic_add v1, v2, s[4:5] offset:1024

.LBB0_14:
	v_readlane_b32 s0, v249, 49
	v_readlane_b32 s4, v249, 47
	v_readlane_b32 s1, v251, 0
	s_cmp_gt_i32 s4, 2
	s_cbranch_scc1 .Lpp_nof
	s_cmp_lg_u32 s84, 0x100
	s_cbranch_scc1 .Lpp_nof
	s_cmp_eq_u32 s0, 9
	s_cbranch_scc1 .Lpp_f9
	s_cmp_lt_u32 s1, 0xc0
	s_cbranch_scc1 .Lpp_nof
	s_cmp_eq_u32 s0, 7
	s_cbranch_scc1 .Lpp_f7
	s_cmp_eq_u32 s0, 10
	s_cbranch_scc0 .Lpp_nof
	s_add_i32 s6, s1, 0xffffff80
	s_branch .Lpp_f
.Lpp_f7:
	s_add_i32 s6, s1, 0xffffff40
	s_branch .Lpp_f
.Lpp_f9:
	s_cmp_lt_u32 s1, 48
	s_cbranch_scc1 .Lpp_nof
	s_cmp_lt_u32 s1, 0xf8
	s_cbranch_scc0 .Lpp_f9f
	s_movk_i32 s101, 0x2000
	s_movk_i32 s100, 0x360
	s_add_i32 s23, s1, 0xffffffd0
	s_movk_i32 s26, 0xc8
	s_add_i32 s4, s4, 1
	s_nop 1
	v_writelane_b32 v249, s4, 47
	v_readlane_b32 s5, v249, 48
	s_mov_b64 s[20:21], -1
	s_mov_b64 s[24:25], -1
	s_mov_b64 s[0:1], -1
	s_branch .Lpp_conv_fb
.Lpp_f9f:
	s_add_i32 s6, s1, 0xffffff88
.Lpp_f:
	s_add_i32 s101, s1, 1
	s_add_i32 s4, s4, 1
	s_nop 1
	v_writelane_b32 v251, s6, 0
	v_writelane_b32 v249, s4, 47
	v_readlane_b32 s5, v249, 48
	s_mov_b64 s[20:21], -1
	s_mov_b64 s[24:25], -1
	s_mov_b64 s[0:1], -1
	s_branch .LBB0_55
.Lpp_nof:
	s_cmp_eq_u32 s0, 0
	s_cselect_b64 s[0:1], -1, 0
	s_cmp_gt_i32 s4, 0
	s_cselect_b64 s[20:21], -1, 0
	s_and_b64 s[20:21], s[0:1], s[20:21]
	v_readlane_b32 s5, v249, 48
	s_andn2_b64 vcc, exec, s[20:21]
	s_cbranch_vccnz .LBB0_352
	s_cmp_lg_u32 s84, 0x100
	s_cbranch_scc1 .LBB0_55
	s_movk_i32 s101, 0x1000
	s_branch .LBB0_55

.LBB0_64:
	s_cmpk_eq_u32 s101, 0x1000
	s_cbranch_scc0 .Lpp_n64
	v_readlane_b32 s23, v251, 0
	s_mov_b32 s26, s84
	s_nop 0
	s_addk_i32 s23, 0x360
	s_branch .Lpp_conv_fb

.Lpp_conv_fb:
	v_mov_b32_e32 v0, v135
	s_cmp_lt_i32 s23, s100
	s_cselect_b64 s[38:39], -1, 0
	s_and_b64 s[0:1], s[38:39], exec
	s_cselect_b32 s34, s23, 0
	s_cmpk_gt_i32 s34, 0x25f
	s_cbranch_scc0 .LBB0_119
	s_cmpk_gt_u32 s34, 0x27f
	s_mov_b64 s[0:1], -1
	s_cbranch_scc0 .LBB0_136
	s_cmpk_gt_u32 s34, 0x29f
	s_cbranch_scc0 .LBB0_133
	s_cmpk_gt_u32 s34, 0x2df
	s_mov_b64 s[36:37], -1
	s_cbranch_scc0 .LBB0_131
	s_cmpk_gt_u32 s34, 0x35f
	s_cbranch_scc0 .LBB0_128
	s_cmpk_gt_u32 s34, 0x4bf
	s_cbranch_scc0 .LBB0_125
	s_cmpk_gt_u32 s34, 0x61f
	s_cbranch_scc0 .LBB0_122
	v_readlane_b32 s0, v249, 47
	v_readlane_b32 s1, v249, 48
	s_ashr_i32 s1, s0, 31
	v_writelane_b32 v249, s0, 47
	s_cmpk_gt_u32 s34, 0x77f
	s_nop 0
	v_writelane_b32 v249, s1, 48
	s_mov_b64 s[0:1], -1
	s_cbranch_scc0 .LBB0_117
	v_readlane_b32 s0, v249, 47
	v_readlane_b32 s1, v249, 48
	v_readlane_b32 s4, v249, 11
	s_add_i32 s20, s34, 0xfffff880
	s_lshl_b64 s[0:1], s[0:1], 19
	v_readlane_b32 s16, v249, 23
	v_readlane_b32 s17, v249, 24
	s_add_u32 s40, s16, s0
	v_readlane_b32 s5, v249, 12
	v_readlane_b32 s6, v249, 13
	v_readlane_b32 s7, v249, 14
	v_readlane_b32 s8, v249, 15
	v_readlane_b32 s9, v249, 16
	v_readlane_b32 s10, v249, 17
	v_readlane_b32 s11, v249, 18
	v_readlane_b32 s12, v249, 19
	v_readlane_b32 s13, v249, 20
	v_readlane_b32 s14, v249, 21
	v_readlane_b32 s15, v249, 22
	v_readlane_b32 s18, v249, 25
	v_readlane_b32 s19, v249, 26
	s_addc_u32 s41, s17, s1
	s_lshr_b32 s29, s20, 2
	s_and_b32 s31, s34, 3
	s_mov_b64 s[0:1], 0

.LBB0_145:
	v_add_u32_e32 v27, 0x4100, v25
	v_add_u32_e32 v30, 0x4108, v25
	v_add_u32_e32 v32, 0x4110, v25
	v_add_u32_e32 v34, 0x4118, v25
	ds_read2_b32 v[28:29], v27 offset1:1
	ds_read2_b32 v[30:31], v30 offset1:1
	ds_read2_b32 v[32:33], v32 offset1:1
	ds_read2_b32 v[34:35], v34 offset1:1
	v_ashrrev_i32_e32 v27, 31, v26
	s_waitcnt lgkmcnt(3)
	v_cvt_pk_bf16_f32 v28, v28, v29
	s_waitcnt lgkmcnt(2)
	v_cvt_pk_bf16_f32 v29, v30, v31
	s_waitcnt lgkmcnt(1)
	v_cvt_pk_bf16_f32 v30, v32, v33
	v_mul_lo_u32 v32, s25, v26
	v_mul_lo_u32 v33, s24, v27
	v_mad_u64_u32 v[26:27], s[24:25], s24, v26, 0
	v_add3_u32 v27, v27, v33, v32
	v_lshl_add_u64 v[26:27], v[26:27], 1, s[20:21]
	v_lshl_add_u64 v[26:27], s[36:37], 1, v[26:27]
	s_add_i32 s23, s23, s26
	v_lshl_add_u64 v[26:27], s[58:59], 1, v[26:27]
	s_add_i32 s34, s34, s26
	s_waitcnt lgkmcnt(0)
	v_cvt_pk_bf16_f32 v31, v34, v35
	v_lshl_add_u64 v[26:27], v[26:27], 0, v[0:1]
	s_cmp_ge_i32 s23, s100
	s_mov_b32 s31, s68
	s_mov_b32 s29, s35
	s_mov_b32 s30, s69
	s_mov_b64 s[36:37], s[60:61]
	s_mov_b64 s[24:25], s[56:57]
	s_mov_b64 s[20:21], s[54:55]
	global_store_dwordx4 v[26:27], v[28:31], off
	s_barrier
	s_cbranch_scc1 .LBB0_205
.LBB0_146:
	v_add_u32_e32 v26, 0x400, v20
	s_cmp_lt_i32 s34, s100
	s_waitcnt vmcnt(0)
	ds_write2_b32 v20, v2, v3 offset1:65
	ds_write2_b32 v20, v4, v5 offset0:130 offset1:195
	s_waitcnt vmcnt(2)
	ds_write2_b32 v26, v6, v7 offset0:4 offset1:69
	ds_write2_b32 v26, v8, v9 offset0:134 offset1:199
	v_add_u32_e32 v26, 0x4000, v20
	s_cselect_b64 s[58:59], -1, 0
	s_waitcnt vmcnt(1)
	ds_write2_b32 v26, v10, v11 offset0:64 offset1:129
	v_add_u32_e32 v26, 0x4200, v20
	s_and_b64 s[54:55], s[58:59], exec
	ds_write2_b32 v26, v12, v13 offset0:66 offset1:131
	v_add_u32_e32 v26, 0x4400, v20
	s_cselect_b32 s71, s34, 0
	s_waitcnt vmcnt(0)
	ds_write2_b32 v26, v14, v15 offset0:68 offset1:133
	v_add_u32_e32 v26, 0x4600, v20
	s_cmpk_gt_i32 s71, 0x25f
	ds_write2_b32 v26, v16, v17 offset0:70 offset1:135
	s_waitcnt lgkmcnt(0)
	s_barrier
	s_cbranch_scc0 .LBB0_174
	s_cmpk_gt_u32 s71, 0x27f
	s_mov_b64 s[66:67], -1
	s_cbranch_scc0 .LBB0_171
	s_cmpk_gt_u32 s71, 0x29f
	s_cbranch_scc0 .LBB0_168
	s_cmpk_gt_u32 s71, 0x2df
	s_mov_b64 s[60:61], -1
	s_cbranch_scc0 .LBB0_166
	s_cmpk_gt_u32 s71, 0x35f
	s_cbranch_scc0 .LBB0_163
	s_cmpk_gt_u32 s71, 0x4bf
	s_cbranch_scc0 .LBB0_160
	s_cmpk_gt_u32 s71, 0x61f
	s_cbranch_scc0 .LBB0_157
	s_cmpk_gt_u32 s71, 0x77f
	s_mov_b64 s[54:55], -1
	s_cbranch_scc0 .LBB0_155
	s_add_i32 s35, s71, 0xfffff880
	s_lshr_b32 s35, s35, 2
	s_and_b32 s68, s71, 3
	s_mov_b64 s[54:55], 0

.LBB0_206:
	s_and_b64 vcc, exec, s[0:1]
	s_cbranch_vccz .LBB0_352
	v_readlane_b32 s0, v251, 0
	s_cmpk_gt_i32 s0, 0x87
	s_mov_b64 s[0:1], -1
	s_cbranch_scc0 .LBB0_307
	v_readlane_b32 s0, v251, 0
	s_add_i32 s23, s0, 0xffffff78
	s_mov_b32 s0, s84
	s_add_i32 s26, s0, 0xffffff78
	v_mov_b32_e32 v0, v135
	s_cmp_lt_i32 s23, s100
	s_cselect_b64 s[38:39], -1, 0
	s_and_b64 s[0:1], s[38:39], exec
	s_cselect_b32 s34, s23, 0
	s_cmpk_gt_i32 s34, 0x25f
	s_cbranch_scc0 .LBB0_219
	s_cmpk_gt_u32 s34, 0x27f
	s_mov_b64 s[0:1], -1
	s_cbranch_scc0 .LBB0_236
	s_cmpk_gt_u32 s34, 0x29f
	s_cbranch_scc0 .LBB0_233
	s_cmpk_gt_u32 s34, 0x2df
	s_mov_b64 s[36:37], -1
	s_cbranch_scc0 .LBB0_231
	s_cmpk_gt_u32 s34, 0x35f
	s_cbranch_scc0 .LBB0_228
	s_cmpk_gt_u32 s34, 0x4bf
	s_cbranch_scc0 .LBB0_225
	s_cmpk_gt_u32 s34, 0x61f
	s_cbranch_scc0 .LBB0_222
	v_readlane_b32 s0, v249, 47
	v_readlane_b32 s1, v249, 48
	s_ashr_i32 s1, s0, 31
	v_writelane_b32 v249, s0, 47
	s_cmpk_gt_u32 s34, 0x77f
	s_nop 0
	v_writelane_b32 v249, s1, 48
	s_mov_b64 s[0:1], -1
	s_cbranch_scc0 .LBB0_217
	v_readlane_b32 s0, v249, 47
	v_readlane_b32 s1, v249, 48
	v_readlane_b32 s4, v249, 11
	s_add_i32 s20, s34, 0xfffff880
	s_lshl_b64 s[0:1], s[0:1], 19
	v_readlane_b32 s16, v249, 23
	v_readlane_b32 s17, v249, 24
	s_add_u32 s40, s16, s0
	v_readlane_b32 s5, v249, 12
	v_readlane_b32 s6, v249, 13
	v_readlane_b32 s7, v249, 14
	v_readlane_b32 s8, v249, 15
	v_readlane_b32 s9, v249, 16
	v_readlane_b32 s10, v249, 17
	v_readlane_b32 s11, v249, 18
	v_readlane_b32 s12, v249, 19
	v_readlane_b32 s13, v249, 20
	v_readlane_b32 s14, v249, 21
	v_readlane_b32 s15, v249, 22
	v_readlane_b32 s18, v249, 25
	v_readlane_b32 s19, v249, 26
	s_addc_u32 s41, s17, s1
	s_lshr_b32 s29, s20, 2
	s_and_b32 s31, s34, 3
	s_mov_b64 s[0:1], 0

.LBB0_352:
	s_cmp_eq_u32 s101, 0
	s_cbranch_scc1 .Lpp_norm
	s_cmpk_eq_u32 s101, 0x1000
	s_cbranch_scc1 .Lpp_clr
	s_cmpk_eq_u32 s101, 0x2000
	s_cbranch_scc0 .Lpp_done
	v_readlane_b32 s4, v249, 47
	s_movk_i32 s100, 0x790
	s_add_i32 s4, s4, -1
	s_nop 1
	v_writelane_b32 v249, s4, 47
	s_branch .Lpp_clr
.Lpp_done:
	v_readlane_b32 s4, v249, 47
	s_add_i32 s1, s101, -1
	s_add_i32 s4, s4, -1
	s_nop 1
	v_writelane_b32 v251, s1, 0
	v_writelane_b32 v249, s4, 47
.Lpp_clr:
	s_mov_b32 s101, 0

.LBB0_1025:
	s_add_i32 s29, s29, 1
	s_mul_i32 s0, s29, s49
	s_mul_hi_u32 s1, s29, s79
	s_add_i32 s1, s1, s0
	s_mul_i32 s0, s29, s79
	s_add_u32 s20, s0, s48
	s_addc_u32 s21, s1, s50
	s_cmp_lg_u32 s56, 1
	s_cbranch_scc1 .Lq_nx
	s_cmp_lg_u32 s79, 0x100
	s_cbranch_scc1 .Lq_nx
	s_cmp_eq_u32 s29, 2
	s_cbranch_scc0 .Lq_r4
	s_cmp_lt_u32 s48, 0xf8
	s_cbranch_scc1 .Lq_nx
	s_mov_b32 s20, 0x7fffffff
	s_mov_b32 s21, 0
	s_branch .Lq_nx
.Lq_r4:
	s_cmp_eq_u32 s29, 4
	s_cbranch_scc0 .Lq_nx
	s_cmp_lt_u32 s48, 32
	s_cbranch_scc1 .Lq_nx
	s_cmp_ge_u32 s48, 48
	s_cbranch_scc1 .Lq_nx
	s_mov_b32 s21, 0
	s_add_i32 s20, s48, 0x3d8
	s_cmp_lt_u32 s48, 40
	s_cbranch_scc1 .Lq_nx
	s_add_i32 s20, s48, 0x2d0
.Lq_nx:
	v_mov_b64_e32 v[2:3], s[46:47]
	v_cmp_ge_i64_e64 s[36:37], s[20:21], v[2:3]
	v_cmp_lt_i64_e64 s[0:1], s[20:21], v[2:3]
	s_and_b64 vcc, exec, s[36:37]
	s_cbranch_vccnz .LBB0_1027
	s_ashr_i32 s21, s20, 31
	s_lshr_b32 s21, s21, 29
	s_add_i32 s21, s20, s21
	s_ashr_i32 s30, s21, 3
	s_and_b32 s21, s21, -8
	s_sub_i32 s20, s20, s21
	s_lshr_b32 s21, s20, 31
	v_readlane_b32 s4, v249, 61
	s_or_b32 s21, s21, s4
	s_mul_i32 s20, s21, s20
	s_add_i32 s20, s20, s30
	s_abs_i32 s30, s20
	v_readlane_b32 s4, v249, 62
	s_mul_hi_u32 s31, s30, s4
	s_mul_i32 s38, s31, s35
	s_sub_i32 s30, s30, s38
	s_ashr_i32 s21, s20, 31
	s_add_i32 s38, s31, 1
	s_sub_i32 s39, s30, s35
	s_cmp_ge_u32 s30, s35
	s_cselect_b32 s31, s38, s31
	s_cselect_b32 s30, s39, s30
	s_add_i32 s38, s31, 1
	s_cmp_ge_u32 s30, s35
	s_cselect_b32 s30, s38, s31
	s_xor_b32 s30, s30, s21
	s_sub_i32 s21, s30, s21
	s_lshl_b32 s31, s21, 3
	s_sub_i32 s30, 48, s31
	s_min_i32 s38, s30, 8
	s_abs_i32 s30, s38
	v_cvt_f32_u32_e32 v0, s30
	s_sub_i32 s43, 0, s30
	s_mul_i32 s21, s21, s35
	s_sub_i32 s20, s20, s21
	v_rcp_iflag_f32_e32 v0, v0
	s_abs_i32 s39, s20
	s_xor_b32 s21, s20, s38
	s_ashr_i32 s21, s21, 31
	v_mul_f32_e32 v0, 0x4f7ffffe, v0
	v_cvt_u32_f32_e32 v0, v0
	s_nop 0
	v_readfirstlane_b32 s44, v0
	s_mul_i32 s43, s43, s44
	s_mul_hi_u32 s43, s44, s43
	s_add_i32 s44, s44, s43
	s_mul_hi_u32 s43, s39, s44
	s_mul_i32 s44, s43, s30
	s_sub_i32 s39, s39, s44
	s_add_i32 s44, s43, 1
	s_sub_i32 s45, s39, s30
	s_cmp_ge_u32 s39, s30
	s_cselect_b32 s43, s44, s43
	s_cselect_b32 s39, s45, s39
	s_add_i32 s44, s43, 1
	s_cmp_ge_u32 s39, s30
	s_cselect_b32 s30, s44, s43
	s_xor_b32 s30, s30, s21
	s_sub_i32 s30, s30, s21
	s_mul_i32 s21, s30, s38
	s_sub_i32 s20, s20, s21
	s_add_i32 s31, s20, s31

.LBB0_1276:
	s_and_b64 vcc, exec, s[0:1]
	s_cbranch_vccz .LBB0_1278
	v_readlane_b32 s0, v251, 29
	v_readlane_b32 s1, v251, 30
	v_add_u32_e32 v0, s24, v143
	v_lshl_or_b32 v150, s42, 7, v219
	v_mul_u32_u24_e32 v0, 0x1600, v0
	v_lshl_add_u32 v150, v150, 1, v0
	v_mov_b32_e32 v130, 0xbfb8aa3b
	v_mov_b32_e32 v131, 0xbfb8aa3b
	v_mov_b32_e32 v132, 1.0
	v_mov_b32_e32 v133, 1.0
	v_pk_mul_f32 v[154:155], v[126:127], v[130:131]
	v_pk_mul_f32 v[156:157], v[128:129], v[130:131]
	v_pk_mul_f32 v[126:127], v[126:127], v[122:123]
	v_pk_mul_f32 v[128:129], v[128:129], v[124:125]
	v_exp_f32_e32 v154, v154
	v_exp_f32_e32 v155, v155
	v_exp_f32_e32 v156, v156
	v_exp_f32_e32 v157, v157
	v_pk_add_f32 v[154:155], v[154:155], v[132:133]
	v_pk_add_f32 v[156:157], v[156:157], v[132:133]
	v_rcp_f32_e32 v154, v154
	v_rcp_f32_e32 v155, v155
	v_rcp_f32_e32 v156, v156
	v_rcp_f32_e32 v157, v157
	v_pk_mul_f32 v[126:127], v[126:127], v[154:155]
	v_pk_mul_f32 v[128:129], v[128:129], v[156:157]
	v_add_u32_e32 v151, 0x0, v150
	v_cvt_pk_bf16_f32 v122, v126, v127
	v_cvt_pk_bf16_f32 v123, v128, v129
	global_store_dwordx2 v151, v[122:123], s[0:1]
	v_pk_mul_f32 v[158:159], v[118:119], v[130:131]
	v_pk_mul_f32 v[160:161], v[120:121], v[130:131]
	v_pk_mul_f32 v[118:119], v[118:119], v[114:115]
	v_pk_mul_f32 v[120:121], v[120:121], v[116:117]
	v_exp_f32_e32 v158, v158
	v_exp_f32_e32 v159, v159
	v_exp_f32_e32 v160, v160
	v_exp_f32_e32 v161, v161
	v_pk_add_f32 v[158:159], v[158:159], v[132:133]
	v_pk_add_f32 v[160:161], v[160:161], v[132:133]
	v_rcp_f32_e32 v158, v158
	v_rcp_f32_e32 v159, v159
	v_rcp_f32_e32 v160, v160
	v_rcp_f32_e32 v161, v161
	v_pk_mul_f32 v[118:119], v[118:119], v[158:159]
	v_pk_mul_f32 v[120:121], v[120:121], v[160:161]
	v_add_u32_e32 v152, 0x16000, v150
	v_cvt_pk_bf16_f32 v114, v118, v119
	v_cvt_pk_bf16_f32 v115, v120, v121
	global_store_dwordx2 v152, v[114:115], s[0:1]
	v_pk_mul_f32 v[154:155], v[110:111], v[130:131]
	v_pk_mul_f32 v[156:157], v[112:113], v[130:131]
	v_pk_mul_f32 v[110:111], v[110:111], v[106:107]
	v_pk_mul_f32 v[112:113], v[112:113], v[108:109]
	v_exp_f32_e32 v154, v154
	v_exp_f32_e32 v155, v155
	v_exp_f32_e32 v156, v156
	v_exp_f32_e32 v157, v157
	v_pk_add_f32 v[154:155], v[154:155], v[132:133]
	v_pk_add_f32 v[156:157], v[156:157], v[132:133]
	v_rcp_f32_e32 v154, v154
	v_rcp_f32_e32 v155, v155
	v_rcp_f32_e32 v156, v156
	v_rcp_f32_e32 v157, v157
	v_pk_mul_f32 v[110:111], v[110:111], v[154:155]
	v_pk_mul_f32 v[112:113], v[112:113], v[156:157]
	v_add_u32_e32 v151, 0x2c000, v150
	v_cvt_pk_bf16_f32 v106, v110, v111
	v_cvt_pk_bf16_f32 v107, v112, v113
	global_store_dwordx2 v151, v[106:107], s[0:1]
	v_pk_mul_f32 v[158:159], v[102:103], v[130:131]
	v_pk_mul_f32 v[160:161], v[104:105], v[130:131]
	v_pk_mul_f32 v[102:103], v[102:103], v[98:99]
	v_pk_mul_f32 v[104:105], v[104:105], v[100:101]
	v_exp_f32_e32 v158, v158
	v_exp_f32_e32 v159, v159
	v_exp_f32_e32 v160, v160
	v_exp_f32_e32 v161, v161
	v_pk_add_f32 v[158:159], v[158:159], v[132:133]
	v_pk_add_f32 v[160:161], v[160:161], v[132:133]
	v_rcp_f32_e32 v158, v158
	v_rcp_f32_e32 v159, v159
	v_rcp_f32_e32 v160, v160
	v_rcp_f32_e32 v161, v161
	v_pk_mul_f32 v[102:103], v[102:103], v[158:159]
	v_pk_mul_f32 v[104:105], v[104:105], v[160:161]
	v_add_u32_e32 v152, 0x42000, v150
	v_cvt_pk_bf16_f32 v98, v102, v103
	v_cvt_pk_bf16_f32 v99, v104, v105
	global_store_dwordx2 v152, v[98:99], s[0:1]
.Lq_epi0:
	v_pk_mul_f32 v[154:155], v[62:63], v[130:131]
	v_pk_mul_f32 v[156:157], v[64:65], v[130:131]
	v_pk_mul_f32 v[62:63], v[62:63], v[58:59]
	v_pk_mul_f32 v[64:65], v[64:65], v[60:61]
	v_exp_f32_e32 v154, v154
	v_exp_f32_e32 v155, v155
	v_exp_f32_e32 v156, v156
	v_exp_f32_e32 v157, v157
	v_pk_add_f32 v[154:155], v[154:155], v[132:133]
	v_pk_add_f32 v[156:157], v[156:157], v[132:133]
	v_rcp_f32_e32 v154, v154
	v_rcp_f32_e32 v155, v155
	v_rcp_f32_e32 v156, v156
	v_rcp_f32_e32 v157, v157
	v_pk_mul_f32 v[62:63], v[62:63], v[154:155]
	v_pk_mul_f32 v[64:65], v[64:65], v[156:157]
	v_add_u32_e32 v151, 0x0, v150
	v_cvt_pk_bf16_f32 v58, v62, v63
	v_cvt_pk_bf16_f32 v59, v64, v65
	global_store_dwordx2 v151, v[58:59], s[0:1] offset:128
	v_pk_mul_f32 v[158:159], v[54:55], v[130:131]
	v_pk_mul_f32 v[160:161], v[56:57], v[130:131]
	v_pk_mul_f32 v[54:55], v[54:55], v[50:51]
	v_pk_mul_f32 v[56:57], v[56:57], v[52:53]
	v_exp_f32_e32 v158, v158
	v_exp_f32_e32 v159, v159
	v_exp_f32_e32 v160, v160
	v_exp_f32_e32 v161, v161
	v_pk_add_f32 v[158:159], v[158:159], v[132:133]
	v_pk_add_f32 v[160:161], v[160:161], v[132:133]
	v_rcp_f32_e32 v158, v158
	v_rcp_f32_e32 v159, v159
	v_rcp_f32_e32 v160, v160
	v_rcp_f32_e32 v161, v161
	v_pk_mul_f32 v[54:55], v[54:55], v[158:159]
	v_pk_mul_f32 v[56:57], v[56:57], v[160:161]
	v_add_u32_e32 v152, 0x16000, v150
	v_cvt_pk_bf16_f32 v50, v54, v55
	v_cvt_pk_bf16_f32 v51, v56, v57
	global_store_dwordx2 v152, v[50:51], s[0:1] offset:128
	v_pk_mul_f32 v[154:155], v[46:47], v[130:131]
	v_pk_mul_f32 v[156:157], v[48:49], v[130:131]
	v_pk_mul_f32 v[46:47], v[46:47], v[42:43]
	v_pk_mul_f32 v[48:49], v[48:49], v[44:45]
	v_exp_f32_e32 v154, v154
	v_exp_f32_e32 v155, v155
	v_exp_f32_e32 v156, v156
	v_exp_f32_e32 v157, v157
	v_pk_add_f32 v[154:155], v[154:155], v[132:133]
	v_pk_add_f32 v[156:157], v[156:157], v[132:133]
	v_rcp_f32_e32 v154, v154
	v_rcp_f32_e32 v155, v155
	v_rcp_f32_e32 v156, v156
	v_rcp_f32_e32 v157, v157
	v_pk_mul_f32 v[46:47], v[46:47], v[154:155]
	v_pk_mul_f32 v[48:49], v[48:49], v[156:157]
	v_add_u32_e32 v151, 0x2c000, v150
	v_cvt_pk_bf16_f32 v42, v46, v47
	v_cvt_pk_bf16_f32 v43, v48, v49
	global_store_dwordx2 v151, v[42:43], s[0:1] offset:128
	v_pk_mul_f32 v[158:159], v[38:39], v[130:131]
	v_pk_mul_f32 v[160:161], v[40:41], v[130:131]
	v_pk_mul_f32 v[38:39], v[38:39], v[34:35]
	v_pk_mul_f32 v[40:41], v[40:41], v[36:37]
	v_exp_f32_e32 v158, v158
	v_exp_f32_e32 v159, v159
	v_exp_f32_e32 v160, v160
	v_exp_f32_e32 v161, v161
	v_pk_add_f32 v[158:159], v[158:159], v[132:133]
	v_pk_add_f32 v[160:161], v[160:161], v[132:133]
	v_rcp_f32_e32 v158, v158
	v_rcp_f32_e32 v159, v159
	v_rcp_f32_e32 v160, v160
	v_rcp_f32_e32 v161, v161
	v_pk_mul_f32 v[38:39], v[38:39], v[158:159]
	v_pk_mul_f32 v[40:41], v[40:41], v[160:161]
	v_add_u32_e32 v152, 0x42000, v150
	v_cvt_pk_bf16_f32 v34, v38, v39
	v_cvt_pk_bf16_f32 v35, v40, v41
	global_store_dwordx2 v152, v[34:35], s[0:1] offset:128
.Lq_epi1:
	v_pk_mul_f32 v[154:155], v[94:95], v[130:131]
	v_pk_mul_f32 v[156:157], v[96:97], v[130:131]
	v_pk_mul_f32 v[94:95], v[94:95], v[90:91]
	v_pk_mul_f32 v[96:97], v[96:97], v[92:93]
	v_exp_f32_e32 v154, v154
	v_exp_f32_e32 v155, v155
	v_exp_f32_e32 v156, v156
	v_exp_f32_e32 v157, v157
	v_pk_add_f32 v[154:155], v[154:155], v[132:133]
	v_pk_add_f32 v[156:157], v[156:157], v[132:133]
	v_rcp_f32_e32 v154, v154
	v_rcp_f32_e32 v155, v155
	v_rcp_f32_e32 v156, v156
	v_rcp_f32_e32 v157, v157
	v_pk_mul_f32 v[94:95], v[94:95], v[154:155]
	v_pk_mul_f32 v[96:97], v[96:97], v[156:157]
	v_add_u32_e32 v151, 0xb0000, v150
	v_cvt_pk_bf16_f32 v90, v94, v95
	v_cvt_pk_bf16_f32 v91, v96, v97
	global_store_dwordx2 v151, v[90:91], s[0:1]
	v_pk_mul_f32 v[158:159], v[86:87], v[130:131]
	v_pk_mul_f32 v[160:161], v[88:89], v[130:131]
	v_pk_mul_f32 v[86:87], v[86:87], v[82:83]
	v_pk_mul_f32 v[88:89], v[88:89], v[84:85]
	v_exp_f32_e32 v158, v158
	v_exp_f32_e32 v159, v159
	v_exp_f32_e32 v160, v160
	v_exp_f32_e32 v161, v161
	v_pk_add_f32 v[158:159], v[158:159], v[132:133]
	v_pk_add_f32 v[160:161], v[160:161], v[132:133]
	v_rcp_f32_e32 v158, v158
	v_rcp_f32_e32 v159, v159
	v_rcp_f32_e32 v160, v160
	v_rcp_f32_e32 v161, v161
	v_pk_mul_f32 v[86:87], v[86:87], v[158:159]
	v_pk_mul_f32 v[88:89], v[88:89], v[160:161]
	v_add_u32_e32 v152, 0xc6000, v150
	v_cvt_pk_bf16_f32 v82, v86, v87
	v_cvt_pk_bf16_f32 v83, v88, v89
	global_store_dwordx2 v152, v[82:83], s[0:1]
	v_pk_mul_f32 v[154:155], v[78:79], v[130:131]
	v_pk_mul_f32 v[156:157], v[80:81], v[130:131]
	v_pk_mul_f32 v[78:79], v[78:79], v[74:75]
	v_pk_mul_f32 v[80:81], v[80:81], v[76:77]
	v_exp_f32_e32 v154, v154
	v_exp_f32_e32 v155, v155
	v_exp_f32_e32 v156, v156
	v_exp_f32_e32 v157, v157
	v_pk_add_f32 v[154:155], v[154:155], v[132:133]
	v_pk_add_f32 v[156:157], v[156:157], v[132:133]
	v_rcp_f32_e32 v154, v154
	v_rcp_f32_e32 v155, v155
	v_rcp_f32_e32 v156, v156
	v_rcp_f32_e32 v157, v157
	v_pk_mul_f32 v[78:79], v[78:79], v[154:155]
	v_pk_mul_f32 v[80:81], v[80:81], v[156:157]
	v_add_u32_e32 v151, 0xdc000, v150
	v_cvt_pk_bf16_f32 v74, v78, v79
	v_cvt_pk_bf16_f32 v75, v80, v81
	global_store_dwordx2 v151, v[74:75], s[0:1]
	v_pk_mul_f32 v[158:159], v[70:71], v[130:131]
	v_pk_mul_f32 v[160:161], v[72:73], v[130:131]
	v_pk_mul_f32 v[70:71], v[70:71], v[66:67]
	v_pk_mul_f32 v[72:73], v[72:73], v[68:69]
	v_exp_f32_e32 v158, v158
	v_exp_f32_e32 v159, v159
	v_exp_f32_e32 v160, v160
	v_exp_f32_e32 v161, v161
	v_pk_add_f32 v[158:159], v[158:159], v[132:133]
	v_pk_add_f32 v[160:161], v[160:161], v[132:133]
	v_rcp_f32_e32 v158, v158
	v_rcp_f32_e32 v159, v159
	v_rcp_f32_e32 v160, v160
	v_rcp_f32_e32 v161, v161
	v_pk_mul_f32 v[70:71], v[70:71], v[158:159]
	v_pk_mul_f32 v[72:73], v[72:73], v[160:161]
	v_add_u32_e32 v152, 0xf2000, v150
	v_cvt_pk_bf16_f32 v66, v70, v71
	v_cvt_pk_bf16_f32 v67, v72, v73
	global_store_dwordx2 v152, v[66:67], s[0:1]
.Lq_epi2:
	v_pk_mul_f32 v[154:155], v[30:31], v[130:131]
	v_pk_mul_f32 v[156:157], v[32:33], v[130:131]
	v_pk_mul_f32 v[30:31], v[30:31], v[26:27]
	v_pk_mul_f32 v[32:33], v[32:33], v[28:29]
	v_exp_f32_e32 v154, v154
	v_exp_f32_e32 v155, v155
	v_exp_f32_e32 v156, v156
	v_exp_f32_e32 v157, v157
	v_pk_add_f32 v[154:155], v[154:155], v[132:133]
	v_pk_add_f32 v[156:157], v[156:157], v[132:133]
	v_rcp_f32_e32 v154, v154
	v_rcp_f32_e32 v155, v155
	v_rcp_f32_e32 v156, v156
	v_rcp_f32_e32 v157, v157
	v_pk_mul_f32 v[30:31], v[30:31], v[154:155]
	v_pk_mul_f32 v[32:33], v[32:33], v[156:157]
	v_add_u32_e32 v151, 0xb0000, v150
	v_cvt_pk_bf16_f32 v26, v30, v31
	v_cvt_pk_bf16_f32 v27, v32, v33
	global_store_dwordx2 v151, v[26:27], s[0:1] offset:128
	v_pk_mul_f32 v[158:159], v[22:23], v[130:131]
	v_pk_mul_f32 v[160:161], v[24:25], v[130:131]
	v_pk_mul_f32 v[22:23], v[22:23], v[18:19]
	v_pk_mul_f32 v[24:25], v[24:25], v[20:21]
	v_exp_f32_e32 v158, v158
	v_exp_f32_e32 v159, v159
	v_exp_f32_e32 v160, v160
	v_exp_f32_e32 v161, v161
	v_pk_add_f32 v[158:159], v[158:159], v[132:133]
	v_pk_add_f32 v[160:161], v[160:161], v[132:133]
	v_rcp_f32_e32 v158, v158
	v_rcp_f32_e32 v159, v159
	v_rcp_f32_e32 v160, v160
	v_rcp_f32_e32 v161, v161
	v_pk_mul_f32 v[22:23], v[22:23], v[158:159]
	v_pk_mul_f32 v[24:25], v[24:25], v[160:161]
	v_add_u32_e32 v152, 0xc6000, v150
	v_cvt_pk_bf16_f32 v18, v22, v23
	v_cvt_pk_bf16_f32 v19, v24, v25
	global_store_dwordx2 v152, v[18:19], s[0:1] offset:128
	v_pk_mul_f32 v[154:155], v[14:15], v[130:131]
	v_pk_mul_f32 v[156:157], v[16:17], v[130:131]
	v_pk_mul_f32 v[14:15], v[14:15], v[10:11]
	v_pk_mul_f32 v[16:17], v[16:17], v[12:13]
	v_exp_f32_e32 v154, v154
	v_exp_f32_e32 v155, v155
	v_exp_f32_e32 v156, v156
	v_exp_f32_e32 v157, v157
	v_pk_add_f32 v[154:155], v[154:155], v[132:133]
	v_pk_add_f32 v[156:157], v[156:157], v[132:133]
	v_rcp_f32_e32 v154, v154
	v_rcp_f32_e32 v155, v155
	v_rcp_f32_e32 v156, v156
	v_rcp_f32_e32 v157, v157
	v_pk_mul_f32 v[14:15], v[14:15], v[154:155]
	v_pk_mul_f32 v[16:17], v[16:17], v[156:157]
	v_add_u32_e32 v151, 0xdc000, v150
	v_cvt_pk_bf16_f32 v10, v14, v15
	v_cvt_pk_bf16_f32 v11, v16, v17
	global_store_dwordx2 v151, v[10:11], s[0:1] offset:128
	v_pk_mul_f32 v[158:159], v[6:7], v[130:131]
	v_pk_mul_f32 v[160:161], v[8:9], v[130:131]
	v_pk_mul_f32 v[6:7], v[6:7], v[2:3]
	v_pk_mul_f32 v[8:9], v[8:9], v[4:5]
	v_exp_f32_e32 v158, v158
	v_exp_f32_e32 v159, v159
	v_exp_f32_e32 v160, v160
	v_exp_f32_e32 v161, v161
	v_pk_add_f32 v[158:159], v[158:159], v[132:133]
	v_pk_add_f32 v[160:161], v[160:161], v[132:133]
	v_rcp_f32_e32 v158, v158
	v_rcp_f32_e32 v159, v159
	v_rcp_f32_e32 v160, v160
	v_rcp_f32_e32 v161, v161
	v_pk_mul_f32 v[6:7], v[6:7], v[158:159]
	v_pk_mul_f32 v[8:9], v[8:9], v[160:161]
	v_add_u32_e32 v152, 0xf2000, v150
	v_cvt_pk_bf16_f32 v2, v6, v7
	v_cvt_pk_bf16_f32 v3, v8, v9
	global_store_dwordx2 v152, v[2:3], s[0:1] offset:128
